# static priority level: waves 0-3 raised to s_setprio 3 instead of 1 (flips deleted as before)
# speedup vs baseline: 1.0084x; 1.0084x over previous
_Z6mk_fwd4Args:
	s_load_dwordx2 s[70:71], s[0:1], 0xe0
	s_load_dword s50, s[0:1], 0xe8
	s_mov_b64 s[76:77], s[0:1]
	s_add_u32 s6, s76, 0xe0
	v_and_b32_e32 v204, 0x3ff, v0
	s_addc_u32 s7, s77, 0
	v_cmp_gt_u32_e32 vcc, 16, v204
	s_and_saveexec_b64 s[0:1], vcc
	v_lshl_add_u32 v1, v204, 2, 0
	v_add_u32_e32 v1, 0x20140, v1
	v_mov_b32_e32 v2, 0
	ds_write_b32 v1, v2
	s_or_b64 exec, exec, s[0:1]
	s_waitcnt lgkmcnt(0)
	s_barrier
	v_readfirstlane_b32 s3, v204
	s_lshr_b32 s3, s3, 8
	s_cmp_eq_u32 s3, 0
	s_cbranch_scc0 .Lprio_static_done
	s_setprio 3
